# P3 k-loop: group-B hook block moved out of line; the common path from the last MFMA to the loop-back barrier is one untaken branch (s_setprio 0 after the barrier)
# baseline (speedup 1.0000x reference)
.Lpeel_mid_p3:
	s_add_i32 s75, 0, 0x18000
	v_add_u32_e32 v1, s75, v173
	s_add_i32 s91, 0, 0x1c000
	ds_read_b128 v[132:135], v1
	ds_read_b128 v[136:139], v1 offset:1024
	ds_read_b128 v[140:143], v1 offset:2048
	ds_read_b128 v[178:181], v1 offset:3072
	v_add_u32_e32 v1, s91, v173
	ds_read_b128 v[182:185], v1
	ds_read_b128 v[188:191], v1 offset:1024
	ds_read_b128 v[192:195], v1 offset:2048
	ds_read_b128 v[196:199], v1 offset:3072
	s_add_u32 s66, s66, 0xa0000
	s_addc_u32 s67, s67, 0
	s_mov_b32 m0, s71
	v_lshl_add_u64 v[6:7], s[66:67], 0, v[150:151]
	ds_read_b128 v[200:203], v174 offset:32768
	ds_read_b128 v[204:207], v174 offset:33792
	ds_read_b128 v[208:211], v174 offset:34816
	ds_read_b128 v[212:215], v174 offset:35840
	ds_read_b128 v[216:219], v174 offset:36864
	ds_read_b128 v[220:223], v174 offset:37888
	ds_read_b128 v[224:227], v174 offset:38912
	ds_read_b128 v[228:231], v174 offset:39936
	global_load_lds_dwordx4 v[6:7], off
	v_lshl_add_u64 v[6:7], s[66:67], 0, v[146:147]
	s_mov_b32 m0, s72
	s_nop 0
	global_load_lds_dwordx4 v[6:7], off
	s_waitcnt vmcnt(8) lgkmcnt(0)
	s_setprio 1
	s_barrier
	v_mfma_f32_16x16x32_bf16 v[128:131], v[132:135], v[200:203], v[128:131]
	v_mfma_f32_16x16x32_bf16 v[124:127], v[140:143], v[200:203], v[124:127]
	v_mfma_f32_16x16x32_bf16 v[112:115], v[132:135], v[208:211], v[112:115]
	v_mfma_f32_16x16x32_bf16 v[108:111], v[140:143], v[208:211], v[108:111]
	v_mfma_f32_16x16x32_bf16 v[96:99], v[132:135], v[216:219], v[96:99]
	v_mfma_f32_16x16x32_bf16 v[92:95], v[140:143], v[216:219], v[92:95]
	v_mfma_f32_16x16x32_bf16 v[80:83], v[132:135], v[224:227], v[80:83]
	v_mfma_f32_16x16x32_bf16 v[76:79], v[140:143], v[224:227], v[76:79]
	v_mfma_f32_16x16x32_bf16 v[128:131], v[136:139], v[204:207], v[128:131]
	v_mfma_f32_16x16x32_bf16 v[124:127], v[178:181], v[204:207], v[124:127]
	v_mfma_f32_16x16x32_bf16 v[112:115], v[136:139], v[212:215], v[112:115]
	v_mfma_f32_16x16x32_bf16 v[108:111], v[178:181], v[212:215], v[108:111]
	v_mfma_f32_16x16x32_bf16 v[96:99], v[136:139], v[220:223], v[96:99]
	v_mfma_f32_16x16x32_bf16 v[92:95], v[178:181], v[220:223], v[92:95]
	v_mfma_f32_16x16x32_bf16 v[80:83], v[136:139], v[228:231], v[80:83]
	v_mfma_f32_16x16x32_bf16 v[76:79], v[178:181], v[228:231], v[76:79]
	s_setprio 0
	s_setprio 1
	v_mfma_f32_16x16x32_bf16 v[120:123], v[182:185], v[200:203], v[120:123]
	v_mfma_f32_16x16x32_bf16 v[116:119], v[192:195], v[200:203], v[116:119]
	v_mfma_f32_16x16x32_bf16 v[104:107], v[182:185], v[208:211], v[104:107]
	v_mfma_f32_16x16x32_bf16 v[100:103], v[192:195], v[208:211], v[100:103]
	v_mfma_f32_16x16x32_bf16 v[88:91], v[182:185], v[216:219], v[88:91]
	v_mfma_f32_16x16x32_bf16 v[84:87], v[192:195], v[216:219], v[84:87]
	v_mfma_f32_16x16x32_bf16 v[72:75], v[182:185], v[224:227], v[72:75]
	v_mfma_f32_16x16x32_bf16 v[68:71], v[192:195], v[224:227], v[68:71]
	v_mfma_f32_16x16x32_bf16 v[120:123], v[188:191], v[204:207], v[120:123]
	v_mfma_f32_16x16x32_bf16 v[116:119], v[196:199], v[204:207], v[116:119]
	v_mfma_f32_16x16x32_bf16 v[104:107], v[188:191], v[212:215], v[104:107]
	v_mfma_f32_16x16x32_bf16 v[100:103], v[196:199], v[212:215], v[100:103]
	v_mfma_f32_16x16x32_bf16 v[88:91], v[188:191], v[220:223], v[88:91]
	v_mfma_f32_16x16x32_bf16 v[84:87], v[196:199], v[220:223], v[84:87]
	v_mfma_f32_16x16x32_bf16 v[72:75], v[188:191], v[228:231], v[72:75]
	v_mfma_f32_16x16x32_bf16 v[68:71], v[196:199], v[228:231], v[68:71]
	s_barrier
	s_setprio 0
	s_add_i32 s66, s75, s68
	v_lshl_add_u64 v[6:7], v[232:233], 0, s[14:15]
	s_mov_b32 m0, s66
	ds_read_b128 v[200:203], v174 offset:49152
	ds_read_b128 v[204:207], v174 offset:50176
	ds_read_b128 v[208:211], v174 offset:51200
	ds_read_b128 v[212:215], v174 offset:52224
	ds_read_b128 v[216:219], v174 offset:53248
	ds_read_b128 v[220:223], v174 offset:54272
	ds_read_b128 v[224:227], v174 offset:55296
	ds_read_b128 v[228:231], v174 offset:56320
	global_load_lds_dwordx4 v[6:7], off
	s_add_i32 m0, s66, 0x2000
	s_add_u32 s64, s64, 0xa0080
	v_lshl_add_u64 v[6:7], v[234:235], 0, s[14:15]
	s_addc_u32 s65, s65, 0
	s_add_i32 s66, s91, s68
	global_load_lds_dwordx4 v[6:7], off
	v_lshl_add_u64 v[6:7], s[64:65], 0, v[148:149]
	s_mov_b32 m0, s66
	s_nop 0
	global_load_lds_dwordx4 v[6:7], off
	v_lshl_add_u64 v[6:7], s[64:65], 0, v[144:145]
	s_add_i32 m0, s66, 0x2000
	s_nop 0
	global_load_lds_dwordx4 v[6:7], off
	v_lshl_add_u64 v[6:7], v[236:237], 0, s[14:15]
	s_mov_b32 m0, s73
	s_nop 0
	global_load_lds_dwordx4 v[6:7], off
	v_lshl_add_u64 v[6:7], v[238:239], 0, s[14:15]
	s_mov_b32 m0, s76
	s_nop 0
	global_load_lds_dwordx4 v[6:7], off
	s_waitcnt vmcnt(8) lgkmcnt(0)
	s_setprio 1
	s_barrier
	v_mfma_f32_16x16x32_bf16 v[64:67], v[132:135], v[200:203], v[64:67]
	v_mfma_f32_16x16x32_bf16 v[60:63], v[140:143], v[200:203], v[60:63]
	v_mfma_f32_16x16x32_bf16 v[48:51], v[132:135], v[208:211], v[48:51]
	v_mfma_f32_16x16x32_bf16 v[44:47], v[140:143], v[208:211], v[44:47]
	v_mfma_f32_16x16x32_bf16 v[32:35], v[132:135], v[216:219], v[32:35]
	v_mfma_f32_16x16x32_bf16 v[28:31], v[140:143], v[216:219], v[28:31]
	v_mfma_f32_16x16x32_bf16 v[16:19], v[132:135], v[224:227], v[16:19]
	v_mfma_f32_16x16x32_bf16 v[12:15], v[140:143], v[224:227], v[12:15]
	v_mfma_f32_16x16x32_bf16 v[64:67], v[136:139], v[204:207], v[64:67]
	v_mfma_f32_16x16x32_bf16 v[60:63], v[178:181], v[204:207], v[60:63]
	v_mfma_f32_16x16x32_bf16 v[48:51], v[136:139], v[212:215], v[48:51]
	s_add_u32 s60, s60, 0x100
	v_mfma_f32_16x16x32_bf16 v[44:47], v[178:181], v[212:215], v[44:47]
	s_addc_u32 s61, s61, 0
	v_mfma_f32_16x16x32_bf16 v[32:35], v[136:139], v[220:223], v[32:35]
	s_cmp_eq_u32 s2, 16
	v_mfma_f32_16x16x32_bf16 v[28:31], v[178:181], v[220:223], v[28:31]
	s_cselect_b32 s100, 1, 0
	v_mfma_f32_16x16x32_bf16 v[16:19], v[136:139], v[228:231], v[16:19]
	s_cmp_eq_u32 s2, 24
	v_mfma_f32_16x16x32_bf16 v[12:15], v[178:181], v[228:231], v[12:15]
	s_cselect_b32 s101, 1, 0
	s_setprio 0
	s_setprio 1
	v_mfma_f32_16x16x32_bf16 v[56:59], v[182:185], v[200:203], v[56:59]
	s_or_b32 s100, s100, s101
	v_mfma_f32_16x16x32_bf16 v[52:55], v[192:195], v[200:203], v[52:55]
	s_cmp_eq_u64 s[62:63], 0
	v_mfma_f32_16x16x32_bf16 v[40:43], v[182:185], v[208:211], v[40:43]
	s_cselect_b32 s100, s100, 0
	v_mfma_f32_16x16x32_bf16 v[36:39], v[192:195], v[208:211], v[36:39]
	s_cmp_ge_i32 s2, s88
	v_mfma_f32_16x16x32_bf16 v[24:27], v[182:185], v[216:219], v[24:27]
	s_cselect_b32 s67, 1, 0
	v_mfma_f32_16x16x32_bf16 v[20:23], v[192:195], v[216:219], v[20:23]
	s_cmp_eq_u64 s[18:19], 0
	v_mfma_f32_16x16x32_bf16 v[6:9], v[182:185], v[224:227], v[8:11]
	s_cselect_b32 s66, 0, s100
	v_mfma_f32_16x16x32_bf16 v[2:5], v[192:195], v[224:227], v[2:5]
	s_cselect_b32 s100, s100, 0
	v_mfma_f32_16x16x32_bf16 v[56:59], v[188:191], v[204:207], v[56:59]
	s_or_b32 s66, s66, s67
	v_mfma_f32_16x16x32_bf16 v[52:55], v[196:199], v[204:207], v[52:55]
	s_mov_b32 s64, s2
	v_mfma_f32_16x16x32_bf16 v[40:43], v[188:191], v[212:215], v[40:43]
	s_cmp_lg_u32 s100, 0
	v_mfma_f32_16x16x32_bf16 v[36:39], v[196:199], v[212:215], v[36:39]
	v_mfma_f32_16x16x32_bf16 v[24:27], v[188:191], v[220:223], v[24:27]
	v_mfma_f32_16x16x32_bf16 v[20:23], v[196:199], v[220:223], v[20:23]
	v_mfma_f32_16x16x32_bf16 v[8:11], v[188:191], v[228:231], v[6:9]
	v_mfma_f32_16x16x32_bf16 v[4:7], v[196:199], v[228:231], v[2:5]
	s_cbranch_scc1 .Lhk_doB
.Lhk_skipB:
	s_barrier
	s_setprio 0
	s_cmp_lg_u32 s66, 0
	s_cbranch_scc1 .Lp3_special
	s_branch .LBB0_599

.Lhk_doB:
	s_setprio 0
	s_cmp_eq_u32 s2, 16
	s_cselect_b32 s99, 0, 1
	s_add_i32 s99, s98, s99
	s_lshl_b32 s99, s99, 17
	s_add_u32 s100, s38, 0xba00000
	s_addc_u32 s101, s39, 0
	s_add_u32 s100, s100, s99
	s_addc_u32 s101, s101, 0
	v_lshrrev_b32_e32 v2, 6, v175
	v_mul_u32_u24_e32 v2, 0x3c00, v2
	v_lshl_add_u32 v2, v175, 4, v2
	v_mov_b32_e32 v3, 0
	v_lshl_add_u64 v[2:3], s[100:101], 0, v[2:3]
	s_mov_b64 s[100:101], 0x20000
	v_lshl_add_u64 v[254:255], v[2:3], 0, s[100:101]
	global_load_dwordx4 v[132:135], v[2:3], off
	global_load_dwordx4 v[136:139], v[2:3], off offset:1024
	global_load_dwordx4 v[140:143], v[254:255], off
	global_load_dwordx4 v[188:191], v[254:255], off offset:1024
	v_lshl_add_u64 v[2:3], v[2:3], 0, s[20:21]
	v_lshl_add_u64 v[254:255], v[254:255], 0, s[20:21]
	global_load_dwordx4 v[192:195], v[2:3], off
	global_load_dwordx4 v[196:199], v[2:3], off offset:1024
	global_load_dwordx4 v[200:203], v[254:255], off
	global_load_dwordx4 v[204:207], v[254:255], off offset:1024
	v_lshl_add_u64 v[2:3], v[2:3], 0, s[20:21]
	v_lshl_add_u64 v[254:255], v[254:255], 0, s[20:21]
	global_load_dwordx4 v[208:211], v[2:3], off
	global_load_dwordx4 v[212:215], v[2:3], off offset:1024
	global_load_dwordx4 v[216:219], v[254:255], off
	global_load_dwordx4 v[220:223], v[254:255], off offset:1024
	v_lshl_add_u64 v[2:3], v[2:3], 0, s[20:21]
	v_lshl_add_u64 v[254:255], v[254:255], 0, s[20:21]
	global_load_dwordx4 v[224:227], v[2:3], off
	global_load_dwordx4 v[228:231], v[2:3], off offset:1024
	global_load_dwordx4 v[232:235], v[254:255], off
	global_load_dwordx4 v[236:239], v[254:255], off offset:1024
	v_lshl_add_u64 v[2:3], v[2:3], 0, s[20:21]
	v_lshl_add_u64 v[254:255], v[254:255], 0, s[20:21]
	s_waitcnt vmcnt(12)
	v_lshlrev_b32_e32 v178, 16, v140
	v_and_b32_e32 v179, 0xffff0000, v140
	v_lshlrev_b32_e32 v180, 16, v141
	v_and_b32_e32 v181, 0xffff0000, v141
	v_lshlrev_b32_e32 v182, 16, v142
	v_and_b32_e32 v183, 0xffff0000, v142
	v_lshlrev_b32_e32 v184, 16, v143
	v_and_b32_e32 v185, 0xffff0000, v143
	v_rcp_f32_e32 v178, v178
	v_rcp_f32_e32 v179, v179
	v_rcp_f32_e32 v180, v180
	v_rcp_f32_e32 v181, v181
	v_rcp_f32_e32 v182, v182
	v_rcp_f32_e32 v183, v183
	v_rcp_f32_e32 v184, v184
	v_rcp_f32_e32 v185, v185
	v_lshlrev_b32_e32 v140, 16, v132
	v_and_b32_e32 v141, 0xffff0000, v132
	v_lshlrev_b32_e32 v142, 16, v133
	v_and_b32_e32 v143, 0xffff0000, v133
	v_lshlrev_b32_e32 v132, 16, v134
	v_and_b32_e32 v133, 0xffff0000, v134
	v_lshlrev_b32_e32 v134, 16, v135
	v_and_b32_e32 v135, 0xffff0000, v135
	v_pk_mul_f32 v[178:179], v[178:179], v[140:141]
	v_pk_mul_f32 v[180:181], v[180:181], v[142:143]
	v_pk_mul_f32 v[182:183], v[182:183], v[132:133]
	v_pk_mul_f32 v[184:185], v[184:185], v[134:135]
	v_pk_mul_f32 v[128:129], v[128:129], v[178:179]
	v_pk_mul_f32 v[130:131], v[130:131], v[180:181]
	v_pk_mul_f32 v[124:125], v[124:125], v[182:183]
	v_pk_mul_f32 v[126:127], v[126:127], v[184:185]
	v_lshlrev_b32_e32 v246, 16, v188
	v_and_b32_e32 v247, 0xffff0000, v188
	v_lshlrev_b32_e32 v248, 16, v189
	v_and_b32_e32 v249, 0xffff0000, v189
	v_lshlrev_b32_e32 v250, 16, v190
	v_and_b32_e32 v251, 0xffff0000, v190
	v_lshlrev_b32_e32 v252, 16, v191
	v_and_b32_e32 v253, 0xffff0000, v191
	v_rcp_f32_e32 v246, v246
	v_rcp_f32_e32 v247, v247
	v_rcp_f32_e32 v248, v248
	v_rcp_f32_e32 v249, v249
	v_rcp_f32_e32 v250, v250
	v_rcp_f32_e32 v251, v251
	v_rcp_f32_e32 v252, v252
	v_rcp_f32_e32 v253, v253
	v_lshlrev_b32_e32 v188, 16, v136
	v_and_b32_e32 v189, 0xffff0000, v136
	v_lshlrev_b32_e32 v190, 16, v137
	v_and_b32_e32 v191, 0xffff0000, v137
	v_lshlrev_b32_e32 v136, 16, v138
	v_and_b32_e32 v137, 0xffff0000, v138
	v_lshlrev_b32_e32 v138, 16, v139
	v_and_b32_e32 v139, 0xffff0000, v139
	v_pk_mul_f32 v[246:247], v[246:247], v[188:189]
	v_pk_mul_f32 v[248:249], v[248:249], v[190:191]
	v_pk_mul_f32 v[250:251], v[250:251], v[136:137]
	v_pk_mul_f32 v[252:253], v[252:253], v[138:139]
	v_pk_mul_f32 v[120:121], v[120:121], v[246:247]
	v_pk_mul_f32 v[122:123], v[122:123], v[248:249]
	v_pk_mul_f32 v[116:117], v[116:117], v[250:251]
	v_pk_mul_f32 v[118:119], v[118:119], v[252:253]
	global_load_dwordx4 v[132:135], v[2:3], off
	global_load_dwordx4 v[136:139], v[2:3], off offset:1024
	global_load_dwordx4 v[140:143], v[254:255], off
	global_load_dwordx4 v[188:191], v[254:255], off offset:1024
	v_lshl_add_u64 v[2:3], v[2:3], 0, s[20:21]
	v_lshl_add_u64 v[254:255], v[254:255], 0, s[20:21]
	s_waitcnt vmcnt(12)
	v_lshlrev_b32_e32 v178, 16, v200
	v_and_b32_e32 v179, 0xffff0000, v200
	v_lshlrev_b32_e32 v180, 16, v201
	v_and_b32_e32 v181, 0xffff0000, v201
	v_lshlrev_b32_e32 v182, 16, v202
	v_and_b32_e32 v183, 0xffff0000, v202
	v_lshlrev_b32_e32 v184, 16, v203
	v_and_b32_e32 v185, 0xffff0000, v203
	v_rcp_f32_e32 v178, v178
	v_rcp_f32_e32 v179, v179
	v_rcp_f32_e32 v180, v180
	v_rcp_f32_e32 v181, v181
	v_rcp_f32_e32 v182, v182
	v_rcp_f32_e32 v183, v183
	v_rcp_f32_e32 v184, v184
	v_rcp_f32_e32 v185, v185
	v_lshlrev_b32_e32 v200, 16, v192
	v_and_b32_e32 v201, 0xffff0000, v192
	v_lshlrev_b32_e32 v202, 16, v193
	v_and_b32_e32 v203, 0xffff0000, v193
	v_lshlrev_b32_e32 v192, 16, v194
	v_and_b32_e32 v193, 0xffff0000, v194
	v_lshlrev_b32_e32 v194, 16, v195
	v_and_b32_e32 v195, 0xffff0000, v195
	v_pk_mul_f32 v[178:179], v[178:179], v[200:201]
	v_pk_mul_f32 v[180:181], v[180:181], v[202:203]
	v_pk_mul_f32 v[182:183], v[182:183], v[192:193]
	v_pk_mul_f32 v[184:185], v[184:185], v[194:195]
	v_pk_mul_f32 v[112:113], v[112:113], v[178:179]
	v_pk_mul_f32 v[114:115], v[114:115], v[180:181]
	v_pk_mul_f32 v[108:109], v[108:109], v[182:183]
	v_pk_mul_f32 v[110:111], v[110:111], v[184:185]
	v_lshlrev_b32_e32 v246, 16, v204
	v_and_b32_e32 v247, 0xffff0000, v204
	v_lshlrev_b32_e32 v248, 16, v205
	v_and_b32_e32 v249, 0xffff0000, v205
	v_lshlrev_b32_e32 v250, 16, v206
	v_and_b32_e32 v251, 0xffff0000, v206
	v_lshlrev_b32_e32 v252, 16, v207
	v_and_b32_e32 v253, 0xffff0000, v207
	v_rcp_f32_e32 v246, v246
	v_rcp_f32_e32 v247, v247
	v_rcp_f32_e32 v248, v248
	v_rcp_f32_e32 v249, v249
	v_rcp_f32_e32 v250, v250
	v_rcp_f32_e32 v251, v251
	v_rcp_f32_e32 v252, v252
	v_rcp_f32_e32 v253, v253
	v_lshlrev_b32_e32 v204, 16, v196
	v_and_b32_e32 v205, 0xffff0000, v196
	v_lshlrev_b32_e32 v206, 16, v197
	v_and_b32_e32 v207, 0xffff0000, v197
	v_lshlrev_b32_e32 v196, 16, v198
	v_and_b32_e32 v197, 0xffff0000, v198
	v_lshlrev_b32_e32 v198, 16, v199
	v_and_b32_e32 v199, 0xffff0000, v199
	v_pk_mul_f32 v[246:247], v[246:247], v[204:205]
	v_pk_mul_f32 v[248:249], v[248:249], v[206:207]
	v_pk_mul_f32 v[250:251], v[250:251], v[196:197]
	v_pk_mul_f32 v[252:253], v[252:253], v[198:199]
	v_pk_mul_f32 v[104:105], v[104:105], v[246:247]
	v_pk_mul_f32 v[106:107], v[106:107], v[248:249]
	v_pk_mul_f32 v[100:101], v[100:101], v[250:251]
	v_pk_mul_f32 v[102:103], v[102:103], v[252:253]
	global_load_dwordx4 v[192:195], v[2:3], off
	global_load_dwordx4 v[196:199], v[2:3], off offset:1024
	global_load_dwordx4 v[200:203], v[254:255], off
	global_load_dwordx4 v[204:207], v[254:255], off offset:1024
	v_lshl_add_u64 v[2:3], v[2:3], 0, s[20:21]
	v_lshl_add_u64 v[254:255], v[254:255], 0, s[20:21]
	s_waitcnt vmcnt(12)
	v_lshlrev_b32_e32 v178, 16, v216
	v_and_b32_e32 v179, 0xffff0000, v216
	v_lshlrev_b32_e32 v180, 16, v217
	v_and_b32_e32 v181, 0xffff0000, v217
	v_lshlrev_b32_e32 v182, 16, v218
	v_and_b32_e32 v183, 0xffff0000, v218
	v_lshlrev_b32_e32 v184, 16, v219
	v_and_b32_e32 v185, 0xffff0000, v219
	v_rcp_f32_e32 v178, v178
	v_rcp_f32_e32 v179, v179
	v_rcp_f32_e32 v180, v180
	v_rcp_f32_e32 v181, v181
	v_rcp_f32_e32 v182, v182
	v_rcp_f32_e32 v183, v183
	v_rcp_f32_e32 v184, v184
	v_rcp_f32_e32 v185, v185
	v_lshlrev_b32_e32 v216, 16, v208
	v_and_b32_e32 v217, 0xffff0000, v208
	v_lshlrev_b32_e32 v218, 16, v209
	v_and_b32_e32 v219, 0xffff0000, v209
	v_lshlrev_b32_e32 v208, 16, v210
	v_and_b32_e32 v209, 0xffff0000, v210
	v_lshlrev_b32_e32 v210, 16, v211
	v_and_b32_e32 v211, 0xffff0000, v211
	v_pk_mul_f32 v[178:179], v[178:179], v[216:217]
	v_pk_mul_f32 v[180:181], v[180:181], v[218:219]
	v_pk_mul_f32 v[182:183], v[182:183], v[208:209]
	v_pk_mul_f32 v[184:185], v[184:185], v[210:211]
	v_pk_mul_f32 v[96:97], v[96:97], v[178:179]
	v_pk_mul_f32 v[98:99], v[98:99], v[180:181]
	v_pk_mul_f32 v[92:93], v[92:93], v[182:183]
	v_pk_mul_f32 v[94:95], v[94:95], v[184:185]
	v_lshlrev_b32_e32 v246, 16, v220
	v_and_b32_e32 v247, 0xffff0000, v220
	v_lshlrev_b32_e32 v248, 16, v221
	v_and_b32_e32 v249, 0xffff0000, v221
	v_lshlrev_b32_e32 v250, 16, v222
	v_and_b32_e32 v251, 0xffff0000, v222
	v_lshlrev_b32_e32 v252, 16, v223
	v_and_b32_e32 v253, 0xffff0000, v223
	v_rcp_f32_e32 v246, v246
	v_rcp_f32_e32 v247, v247
	v_rcp_f32_e32 v248, v248
	v_rcp_f32_e32 v249, v249
	v_rcp_f32_e32 v250, v250
	v_rcp_f32_e32 v251, v251
	v_rcp_f32_e32 v252, v252
	v_rcp_f32_e32 v253, v253
	v_lshlrev_b32_e32 v220, 16, v212
	v_and_b32_e32 v221, 0xffff0000, v212
	v_lshlrev_b32_e32 v222, 16, v213
	v_and_b32_e32 v223, 0xffff0000, v213
	v_lshlrev_b32_e32 v212, 16, v214
	v_and_b32_e32 v213, 0xffff0000, v214
	v_lshlrev_b32_e32 v214, 16, v215
	v_and_b32_e32 v215, 0xffff0000, v215
	v_pk_mul_f32 v[246:247], v[246:247], v[220:221]
	v_pk_mul_f32 v[248:249], v[248:249], v[222:223]
	v_pk_mul_f32 v[250:251], v[250:251], v[212:213]
	v_pk_mul_f32 v[252:253], v[252:253], v[214:215]
	v_pk_mul_f32 v[88:89], v[88:89], v[246:247]
	v_pk_mul_f32 v[90:91], v[90:91], v[248:249]
	v_pk_mul_f32 v[84:85], v[84:85], v[250:251]
	v_pk_mul_f32 v[86:87], v[86:87], v[252:253]
	global_load_dwordx4 v[208:211], v[2:3], off
	global_load_dwordx4 v[212:215], v[2:3], off offset:1024
	global_load_dwordx4 v[216:219], v[254:255], off
	global_load_dwordx4 v[220:223], v[254:255], off offset:1024
	v_lshl_add_u64 v[2:3], v[2:3], 0, s[20:21]
	v_lshl_add_u64 v[254:255], v[254:255], 0, s[20:21]
	s_waitcnt vmcnt(12)
	v_lshlrev_b32_e32 v178, 16, v232
	v_and_b32_e32 v179, 0xffff0000, v232
	v_lshlrev_b32_e32 v180, 16, v233
	v_and_b32_e32 v181, 0xffff0000, v233
	v_lshlrev_b32_e32 v182, 16, v234
	v_and_b32_e32 v183, 0xffff0000, v234
	v_lshlrev_b32_e32 v184, 16, v235
	v_and_b32_e32 v185, 0xffff0000, v235
	v_rcp_f32_e32 v178, v178
	v_rcp_f32_e32 v179, v179
	v_rcp_f32_e32 v180, v180
	v_rcp_f32_e32 v181, v181
	v_rcp_f32_e32 v182, v182
	v_rcp_f32_e32 v183, v183
	v_rcp_f32_e32 v184, v184
	v_rcp_f32_e32 v185, v185
	v_lshlrev_b32_e32 v232, 16, v224
	v_and_b32_e32 v233, 0xffff0000, v224
	v_lshlrev_b32_e32 v234, 16, v225
	v_and_b32_e32 v235, 0xffff0000, v225
	v_lshlrev_b32_e32 v224, 16, v226
	v_and_b32_e32 v225, 0xffff0000, v226
	v_lshlrev_b32_e32 v226, 16, v227
	v_and_b32_e32 v227, 0xffff0000, v227
	v_pk_mul_f32 v[178:179], v[178:179], v[232:233]
	v_pk_mul_f32 v[180:181], v[180:181], v[234:235]
	v_pk_mul_f32 v[182:183], v[182:183], v[224:225]
	v_pk_mul_f32 v[184:185], v[184:185], v[226:227]
	v_pk_mul_f32 v[80:81], v[80:81], v[178:179]
	v_pk_mul_f32 v[82:83], v[82:83], v[180:181]
	v_pk_mul_f32 v[76:77], v[76:77], v[182:183]
	v_pk_mul_f32 v[78:79], v[78:79], v[184:185]
	v_lshlrev_b32_e32 v246, 16, v236
	v_and_b32_e32 v247, 0xffff0000, v236
	v_lshlrev_b32_e32 v248, 16, v237
	v_and_b32_e32 v249, 0xffff0000, v237
	v_lshlrev_b32_e32 v250, 16, v238
	v_and_b32_e32 v251, 0xffff0000, v238
	v_lshlrev_b32_e32 v252, 16, v239
	v_and_b32_e32 v253, 0xffff0000, v239
	v_rcp_f32_e32 v246, v246
	v_rcp_f32_e32 v247, v247
	v_rcp_f32_e32 v248, v248
	v_rcp_f32_e32 v249, v249
	v_rcp_f32_e32 v250, v250
	v_rcp_f32_e32 v251, v251
	v_rcp_f32_e32 v252, v252
	v_rcp_f32_e32 v253, v253
	v_lshlrev_b32_e32 v236, 16, v228
	v_and_b32_e32 v237, 0xffff0000, v228
	v_lshlrev_b32_e32 v238, 16, v229
	v_and_b32_e32 v239, 0xffff0000, v229
	v_lshlrev_b32_e32 v228, 16, v230
	v_and_b32_e32 v229, 0xffff0000, v230
	v_lshlrev_b32_e32 v230, 16, v231
	v_and_b32_e32 v231, 0xffff0000, v231
	v_pk_mul_f32 v[246:247], v[246:247], v[236:237]
	v_pk_mul_f32 v[248:249], v[248:249], v[238:239]
	v_pk_mul_f32 v[250:251], v[250:251], v[228:229]
	v_pk_mul_f32 v[252:253], v[252:253], v[230:231]
	v_pk_mul_f32 v[72:73], v[72:73], v[246:247]
	v_pk_mul_f32 v[74:75], v[74:75], v[248:249]
	v_pk_mul_f32 v[68:69], v[68:69], v[250:251]
	v_pk_mul_f32 v[70:71], v[70:71], v[252:253]
	global_load_dwordx4 v[224:227], v[2:3], off
	global_load_dwordx4 v[228:231], v[2:3], off offset:1024
	global_load_dwordx4 v[232:235], v[254:255], off
	global_load_dwordx4 v[236:239], v[254:255], off offset:1024
	s_waitcnt vmcnt(12)
	v_lshlrev_b32_e32 v178, 16, v140
	v_and_b32_e32 v179, 0xffff0000, v140
	v_lshlrev_b32_e32 v180, 16, v141
	v_and_b32_e32 v181, 0xffff0000, v141
	v_lshlrev_b32_e32 v182, 16, v142
	v_and_b32_e32 v183, 0xffff0000, v142
	v_lshlrev_b32_e32 v184, 16, v143
	v_and_b32_e32 v185, 0xffff0000, v143
	v_rcp_f32_e32 v178, v178
	v_rcp_f32_e32 v179, v179
	v_rcp_f32_e32 v180, v180
	v_rcp_f32_e32 v181, v181
	v_rcp_f32_e32 v182, v182
	v_rcp_f32_e32 v183, v183
	v_rcp_f32_e32 v184, v184
	v_rcp_f32_e32 v185, v185
	v_lshlrev_b32_e32 v140, 16, v132
	v_and_b32_e32 v141, 0xffff0000, v132
	v_lshlrev_b32_e32 v142, 16, v133
	v_and_b32_e32 v143, 0xffff0000, v133
	v_lshlrev_b32_e32 v132, 16, v134
	v_and_b32_e32 v133, 0xffff0000, v134
	v_lshlrev_b32_e32 v134, 16, v135
	v_and_b32_e32 v135, 0xffff0000, v135
	v_pk_mul_f32 v[178:179], v[178:179], v[140:141]
	v_pk_mul_f32 v[180:181], v[180:181], v[142:143]
	v_pk_mul_f32 v[182:183], v[182:183], v[132:133]
	v_pk_mul_f32 v[184:185], v[184:185], v[134:135]
	v_pk_mul_f32 v[64:65], v[64:65], v[178:179]
	v_pk_mul_f32 v[66:67], v[66:67], v[180:181]
	v_pk_mul_f32 v[60:61], v[60:61], v[182:183]
	v_pk_mul_f32 v[62:63], v[62:63], v[184:185]
	v_lshlrev_b32_e32 v246, 16, v188
	v_and_b32_e32 v247, 0xffff0000, v188
	v_lshlrev_b32_e32 v248, 16, v189
	v_and_b32_e32 v249, 0xffff0000, v189
	v_lshlrev_b32_e32 v250, 16, v190
	v_and_b32_e32 v251, 0xffff0000, v190
	v_lshlrev_b32_e32 v252, 16, v191
	v_and_b32_e32 v253, 0xffff0000, v191
	v_rcp_f32_e32 v246, v246
	v_rcp_f32_e32 v247, v247
	v_rcp_f32_e32 v248, v248
	v_rcp_f32_e32 v249, v249
	v_rcp_f32_e32 v250, v250
	v_rcp_f32_e32 v251, v251
	v_rcp_f32_e32 v252, v252
	v_rcp_f32_e32 v253, v253
	v_lshlrev_b32_e32 v188, 16, v136
	v_and_b32_e32 v189, 0xffff0000, v136
	v_lshlrev_b32_e32 v190, 16, v137
	v_and_b32_e32 v191, 0xffff0000, v137
	v_lshlrev_b32_e32 v136, 16, v138
	v_and_b32_e32 v137, 0xffff0000, v138
	v_lshlrev_b32_e32 v138, 16, v139
	v_and_b32_e32 v139, 0xffff0000, v139
	v_pk_mul_f32 v[246:247], v[246:247], v[188:189]
	v_pk_mul_f32 v[248:249], v[248:249], v[190:191]
	v_pk_mul_f32 v[250:251], v[250:251], v[136:137]
	v_pk_mul_f32 v[252:253], v[252:253], v[138:139]
	v_pk_mul_f32 v[56:57], v[56:57], v[246:247]
	v_pk_mul_f32 v[58:59], v[58:59], v[248:249]
	v_pk_mul_f32 v[52:53], v[52:53], v[250:251]
	v_pk_mul_f32 v[54:55], v[54:55], v[252:253]
	s_waitcnt vmcnt(8)
	v_lshlrev_b32_e32 v178, 16, v200
	v_and_b32_e32 v179, 0xffff0000, v200
	v_lshlrev_b32_e32 v180, 16, v201
	v_and_b32_e32 v181, 0xffff0000, v201
	v_lshlrev_b32_e32 v182, 16, v202
	v_and_b32_e32 v183, 0xffff0000, v202
	v_lshlrev_b32_e32 v184, 16, v203
	v_and_b32_e32 v185, 0xffff0000, v203
	v_rcp_f32_e32 v178, v178
	v_rcp_f32_e32 v179, v179
	v_rcp_f32_e32 v180, v180
	v_rcp_f32_e32 v181, v181
	v_rcp_f32_e32 v182, v182
	v_rcp_f32_e32 v183, v183
	v_rcp_f32_e32 v184, v184
	v_rcp_f32_e32 v185, v185
	v_lshlrev_b32_e32 v200, 16, v192
	v_and_b32_e32 v201, 0xffff0000, v192
	v_lshlrev_b32_e32 v202, 16, v193
	v_and_b32_e32 v203, 0xffff0000, v193
	v_lshlrev_b32_e32 v192, 16, v194
	v_and_b32_e32 v193, 0xffff0000, v194
	v_lshlrev_b32_e32 v194, 16, v195
	v_and_b32_e32 v195, 0xffff0000, v195
	v_pk_mul_f32 v[178:179], v[178:179], v[200:201]
	v_pk_mul_f32 v[180:181], v[180:181], v[202:203]
	v_pk_mul_f32 v[182:183], v[182:183], v[192:193]
	v_pk_mul_f32 v[184:185], v[184:185], v[194:195]
	v_pk_mul_f32 v[48:49], v[48:49], v[178:179]
	v_pk_mul_f32 v[50:51], v[50:51], v[180:181]
	v_pk_mul_f32 v[44:45], v[44:45], v[182:183]
	v_pk_mul_f32 v[46:47], v[46:47], v[184:185]
	v_lshlrev_b32_e32 v246, 16, v204
	v_and_b32_e32 v247, 0xffff0000, v204
	v_lshlrev_b32_e32 v248, 16, v205
	v_and_b32_e32 v249, 0xffff0000, v205
	v_lshlrev_b32_e32 v250, 16, v206
	v_and_b32_e32 v251, 0xffff0000, v206
	v_lshlrev_b32_e32 v252, 16, v207
	v_and_b32_e32 v253, 0xffff0000, v207
	v_rcp_f32_e32 v246, v246
	v_rcp_f32_e32 v247, v247
	v_rcp_f32_e32 v248, v248
	v_rcp_f32_e32 v249, v249
	v_rcp_f32_e32 v250, v250
	v_rcp_f32_e32 v251, v251
	v_rcp_f32_e32 v252, v252
	v_rcp_f32_e32 v253, v253
	v_lshlrev_b32_e32 v204, 16, v196
	v_and_b32_e32 v205, 0xffff0000, v196
	v_lshlrev_b32_e32 v206, 16, v197
	v_and_b32_e32 v207, 0xffff0000, v197
	v_lshlrev_b32_e32 v196, 16, v198
	v_and_b32_e32 v197, 0xffff0000, v198
	v_lshlrev_b32_e32 v198, 16, v199
	v_and_b32_e32 v199, 0xffff0000, v199
	v_pk_mul_f32 v[246:247], v[246:247], v[204:205]
	v_pk_mul_f32 v[248:249], v[248:249], v[206:207]
	v_pk_mul_f32 v[250:251], v[250:251], v[196:197]
	v_pk_mul_f32 v[252:253], v[252:253], v[198:199]
	v_pk_mul_f32 v[40:41], v[40:41], v[246:247]
	v_pk_mul_f32 v[42:43], v[42:43], v[248:249]
	v_pk_mul_f32 v[36:37], v[36:37], v[250:251]
	v_pk_mul_f32 v[38:39], v[38:39], v[252:253]
	s_waitcnt vmcnt(4)
	v_lshlrev_b32_e32 v178, 16, v216
	v_and_b32_e32 v179, 0xffff0000, v216
	v_lshlrev_b32_e32 v180, 16, v217
	v_and_b32_e32 v181, 0xffff0000, v217
	v_lshlrev_b32_e32 v182, 16, v218
	v_and_b32_e32 v183, 0xffff0000, v218
	v_lshlrev_b32_e32 v184, 16, v219
	v_and_b32_e32 v185, 0xffff0000, v219
	v_rcp_f32_e32 v178, v178
	v_rcp_f32_e32 v179, v179
	v_rcp_f32_e32 v180, v180
	v_rcp_f32_e32 v181, v181
	v_rcp_f32_e32 v182, v182
	v_rcp_f32_e32 v183, v183
	v_rcp_f32_e32 v184, v184
	v_rcp_f32_e32 v185, v185
	v_lshlrev_b32_e32 v216, 16, v208
	v_and_b32_e32 v217, 0xffff0000, v208
	v_lshlrev_b32_e32 v218, 16, v209
	v_and_b32_e32 v219, 0xffff0000, v209
	v_lshlrev_b32_e32 v208, 16, v210
	v_and_b32_e32 v209, 0xffff0000, v210
	v_lshlrev_b32_e32 v210, 16, v211
	v_and_b32_e32 v211, 0xffff0000, v211
	v_pk_mul_f32 v[178:179], v[178:179], v[216:217]
	v_pk_mul_f32 v[180:181], v[180:181], v[218:219]
	v_pk_mul_f32 v[182:183], v[182:183], v[208:209]
	v_pk_mul_f32 v[184:185], v[184:185], v[210:211]
	v_pk_mul_f32 v[32:33], v[32:33], v[178:179]
	v_pk_mul_f32 v[34:35], v[34:35], v[180:181]
	v_pk_mul_f32 v[28:29], v[28:29], v[182:183]
	v_pk_mul_f32 v[30:31], v[30:31], v[184:185]
	v_lshlrev_b32_e32 v246, 16, v220
	v_and_b32_e32 v247, 0xffff0000, v220
	v_lshlrev_b32_e32 v248, 16, v221
	v_and_b32_e32 v249, 0xffff0000, v221
	v_lshlrev_b32_e32 v250, 16, v222
	v_and_b32_e32 v251, 0xffff0000, v222
	v_lshlrev_b32_e32 v252, 16, v223
	v_and_b32_e32 v253, 0xffff0000, v223
	v_rcp_f32_e32 v246, v246
	v_rcp_f32_e32 v247, v247
	v_rcp_f32_e32 v248, v248
	v_rcp_f32_e32 v249, v249
	v_rcp_f32_e32 v250, v250
	v_rcp_f32_e32 v251, v251
	v_rcp_f32_e32 v252, v252
	v_rcp_f32_e32 v253, v253
	v_lshlrev_b32_e32 v220, 16, v212
	v_and_b32_e32 v221, 0xffff0000, v212
	v_lshlrev_b32_e32 v222, 16, v213
	v_and_b32_e32 v223, 0xffff0000, v213
	v_lshlrev_b32_e32 v212, 16, v214
	v_and_b32_e32 v213, 0xffff0000, v214
	v_lshlrev_b32_e32 v214, 16, v215
	v_and_b32_e32 v215, 0xffff0000, v215
	v_pk_mul_f32 v[246:247], v[246:247], v[220:221]
	v_pk_mul_f32 v[248:249], v[248:249], v[222:223]
	v_pk_mul_f32 v[250:251], v[250:251], v[212:213]
	v_pk_mul_f32 v[252:253], v[252:253], v[214:215]
	v_pk_mul_f32 v[24:25], v[24:25], v[246:247]
	v_pk_mul_f32 v[26:27], v[26:27], v[248:249]
	v_pk_mul_f32 v[20:21], v[20:21], v[250:251]
	v_pk_mul_f32 v[22:23], v[22:23], v[252:253]
	s_waitcnt vmcnt(0)
	v_lshlrev_b32_e32 v178, 16, v232
	v_and_b32_e32 v179, 0xffff0000, v232
	v_lshlrev_b32_e32 v180, 16, v233
	v_and_b32_e32 v181, 0xffff0000, v233
	v_lshlrev_b32_e32 v182, 16, v234
	v_and_b32_e32 v183, 0xffff0000, v234
	v_lshlrev_b32_e32 v184, 16, v235
	v_and_b32_e32 v185, 0xffff0000, v235
	v_rcp_f32_e32 v178, v178
	v_rcp_f32_e32 v179, v179
	v_rcp_f32_e32 v180, v180
	v_rcp_f32_e32 v181, v181
	v_rcp_f32_e32 v182, v182
	v_rcp_f32_e32 v183, v183
	v_rcp_f32_e32 v184, v184
	v_rcp_f32_e32 v185, v185
	v_lshlrev_b32_e32 v232, 16, v224
	v_and_b32_e32 v233, 0xffff0000, v224
	v_lshlrev_b32_e32 v234, 16, v225
	v_and_b32_e32 v235, 0xffff0000, v225
	v_lshlrev_b32_e32 v224, 16, v226
	v_and_b32_e32 v225, 0xffff0000, v226
	v_lshlrev_b32_e32 v226, 16, v227
	v_and_b32_e32 v227, 0xffff0000, v227
	v_pk_mul_f32 v[178:179], v[178:179], v[232:233]
	v_pk_mul_f32 v[180:181], v[180:181], v[234:235]
	v_pk_mul_f32 v[182:183], v[182:183], v[224:225]
	v_pk_mul_f32 v[184:185], v[184:185], v[226:227]
	v_pk_mul_f32 v[16:17], v[16:17], v[178:179]
	v_pk_mul_f32 v[18:19], v[18:19], v[180:181]
	v_pk_mul_f32 v[12:13], v[12:13], v[182:183]
	v_pk_mul_f32 v[14:15], v[14:15], v[184:185]
	v_lshlrev_b32_e32 v246, 16, v236
	v_and_b32_e32 v247, 0xffff0000, v236
	v_lshlrev_b32_e32 v248, 16, v237
	v_and_b32_e32 v249, 0xffff0000, v237
	v_lshlrev_b32_e32 v250, 16, v238
	v_and_b32_e32 v251, 0xffff0000, v238
	v_lshlrev_b32_e32 v252, 16, v239
	v_and_b32_e32 v253, 0xffff0000, v239
	v_rcp_f32_e32 v246, v246
	v_rcp_f32_e32 v247, v247
	v_rcp_f32_e32 v248, v248
	v_rcp_f32_e32 v249, v249
	v_rcp_f32_e32 v250, v250
	v_rcp_f32_e32 v251, v251
	v_rcp_f32_e32 v252, v252
	v_rcp_f32_e32 v253, v253
	v_lshlrev_b32_e32 v236, 16, v228
	v_and_b32_e32 v237, 0xffff0000, v228
	v_lshlrev_b32_e32 v238, 16, v229
	v_and_b32_e32 v239, 0xffff0000, v229
	v_lshlrev_b32_e32 v228, 16, v230
	v_and_b32_e32 v229, 0xffff0000, v230
	v_lshlrev_b32_e32 v230, 16, v231
	v_and_b32_e32 v231, 0xffff0000, v231
	v_pk_mul_f32 v[246:247], v[246:247], v[236:237]
	v_pk_mul_f32 v[248:249], v[248:249], v[238:239]
	v_pk_mul_f32 v[250:251], v[250:251], v[228:229]
	v_pk_mul_f32 v[252:253], v[252:253], v[230:231]
	v_pk_mul_f32 v[8:9], v[8:9], v[246:247]
	v_pk_mul_f32 v[10:11], v[10:11], v[248:249]
	v_pk_mul_f32 v[4:5], v[4:5], v[250:251]
	v_pk_mul_f32 v[6:7], v[6:7], v[252:253]
	s_branch .Lhk_skipB
